# software pipelining extended to the remaining weight-conversion tile loops
# baseline (speedup 1.0000x reference)
.LBB0_476:
	s_nop 0
	v_mov_b32_e32 v4, v197
	s_and_b64 vcc, exec, s[8:9]
	s_cbranch_vccnz .LBB0_480
	s_sub_i32 s6, s2, s1
	s_cmpk_gt_i32 s6, 0x2bf
	s_cbranch_scc1 .LBB0_480
	v_readlane_b32 s10, v254, 41
	v_readlane_b32 s11, v254, 42
	s_load_dwordx2 s[10:11], s[10:11], 0x108
	s_mul_i32 s12, s46, 0xb00000
	s_mul_hi_u32 s7, s46, 0xb00000
	v_ashrrev_i32_e32 v1, 4, v4
	v_ashrrev_i32_e32 v3, 3, v4
	s_waitcnt lgkmcnt(0)
	s_add_u32 s10, s10, s12
	s_addc_u32 s11, s11, s7
	s_bitcmp0_b32 s46, 0
	s_mov_b32 s3, 0x2d98100
	v_lshlrev_b32_e32 v5, 3, v4
	v_lshlrev_b32_e32 v4, 2, v4
	s_cselect_b32 s7, s3, 0x20d98100
	v_and_b32_e32 v4, 60, v4
	s_movk_i32 s3, 0x110
	s_waitcnt vmcnt(0)
	v_and_b32_e32 v6, 56, v5
	v_lshlrev_b32_e32 v5, 2, v4
	v_mul_lo_u32 v7, v1, s3
	s_add_u32 s12, s4, s7
	v_add3_u32 v8, 0, v5, v7
	v_add3_u32 v9, 0, v7, v5
	v_lshl_add_u32 v5, v3, 2, 0
	v_mul_u32_u24_e32 v7, 0x110, v6
	s_addc_u32 s13, s5, 0
	s_lshl_b32 s7, s6, 6
	s_lshl_b32 s20, s0, 6
	v_lshlrev_b32_e32 v4, 2, v4
	v_add_u32_e32 v10, v5, v7
	v_lshlrev_b32_e32 v6, 1, v6
	v_mov_b32_e32 v96, v4
	s_mul_hi_i32 s60, s6, 0x2e8ba2e9
	s_lshr_b32 s61, s60, 31
	s_ashr_i32 s60, s60, 3
	s_add_i32 s61, s60, s61
	s_mul_i32 s60, s61, 0xfffff500
	s_add_i32 s60, s7, s60
	v_add_u32_e32 v92, s60, v1
	v_ashrrev_i32_e32 v93, 31, v92
	s_lshl_b32 s62, s61, 6
	v_lshlrev_b64 v[88:89], 12, v[92:93]
	v_add_u32_e32 v92, 32, v92
	s_ashr_i32 s63, s62, 31
	v_ashrrev_i32_e32 v93, 31, v92
	v_lshl_add_u64 v[88:89], s[10:11], 0, v[88:89]
	s_lshl_b64 s[64:65], s[62:63], 2
	v_lshlrev_b64 v[92:93], 12, v[92:93]
	v_lshl_add_u64 v[88:89], v[88:89], 0, s[64:65]
	v_mov_b32_e32 v97, v2
	v_lshl_add_u64 v[92:93], s[10:11], 0, v[92:93]
	v_lshl_add_u64 v[88:89], v[88:89], 0, v[96:97]
	v_lshl_add_u64 v[92:93], v[92:93], 0, s[64:65]
	global_load_dwordx4 v[88:91], v[88:89], off
	v_lshl_add_u64 v[92:93], v[92:93], 0, v[96:97]
	global_load_dwordx4 v[92:95], v[92:93], off
	s_waitcnt vmcnt(0)
.LBB0_479:
	s_mov_b32 s14, s60
	s_mov_b32 s15, s61
	s_mov_b32 s16, s62
	s_mov_b32 s17, s63
	s_mov_b32 s18, s64
	s_mov_b32 s19, s65
	s_barrier
	v_add_u32_e32 v5, 0x400, v10
	s_ashr_i32 s15, s14, 31
	v_mov_b32_e32 v7, v2
	s_add_i32 s6, s6, s0
	s_add_i32 s7, s7, s20
	s_cmpk_lt_i32 s6, 0x2c0
	s_waitcnt vmcnt(2)
	ds_write_b128 v8, v[88:91]
	s_waitcnt vmcnt(1)
	ds_write_b128 v9, v[92:95] offset:8704
	s_cbranch_scc0 .Lcvq3_skip
	v_mov_b32_e32 v96, v4
	s_mul_hi_i32 s60, s6, 0x2e8ba2e9
	s_lshr_b32 s61, s60, 31
	s_ashr_i32 s60, s60, 3
	s_add_i32 s61, s60, s61
	s_mul_i32 s60, s61, 0xfffff500
	s_add_i32 s60, s7, s60
	v_add_u32_e32 v92, s60, v1
	v_ashrrev_i32_e32 v93, 31, v92
	s_lshl_b32 s62, s61, 6
	v_lshlrev_b64 v[88:89], 12, v[92:93]
	v_add_u32_e32 v92, 32, v92
	s_ashr_i32 s63, s62, 31
	v_ashrrev_i32_e32 v93, 31, v92
	v_lshl_add_u64 v[88:89], s[10:11], 0, v[88:89]
	s_lshl_b64 s[64:65], s[62:63], 2
	v_lshlrev_b64 v[92:93], 12, v[92:93]
	v_lshl_add_u64 v[88:89], v[88:89], 0, s[64:65]
	v_mov_b32_e32 v97, v2
	v_lshl_add_u64 v[92:93], s[10:11], 0, v[92:93]
	v_lshl_add_u64 v[88:89], v[88:89], 0, v[96:97]
	v_lshl_add_u64 v[92:93], v[92:93], 0, s[64:65]
	global_load_dwordx4 v[88:91], v[88:89], off
	v_lshl_add_u64 v[92:93], v[92:93], 0, v[96:97]
	global_load_dwordx4 v[92:95], v[92:93], off
.Lcvq3_skip:
	s_waitcnt lgkmcnt(0)
	s_barrier
	ds_read2_b32 v[16:17], v10 offset1:68
	ds_read2_b32 v[12:13], v10 offset0:136 offset1:204
	ds_read2_b32 v[18:19], v5 offset0:16 offset1:84
	ds_read2_b32 v[14:15], v5 offset0:152 offset1:220
	v_add_u32_e32 v5, s16, v3
	s_waitcnt lgkmcnt(2)
	v_cvt_pk_f16_f32 v13, v12, v13
	v_cvt_pk_f16_f32 v12, v16, v17
	v_mov_b64_e32 v[16:17], s[12:13]
	v_mad_i64_i32 v[16:17], s[16:17], v5, s59, v[16:17]
	v_lshl_add_u64 v[16:17], s[14:15], 1, v[16:17]
	s_waitcnt lgkmcnt(0)
	v_cvt_pk_f16_f32 v15, v14, v15
	v_cvt_pk_f16_f32 v14, v18, v19
	v_lshl_add_u64 v[16:17], v[16:17], 0, v[6:7]
	global_store_dwordx4 v[16:17], v[12:15], off
	s_cmpk_lt_i32 s6, 0x2c0
	s_cbranch_scc1 .LBB0_479
.LBB0_480:
	s_lshl_b64 s[10:11], s[46:47], 20
	v_mov_b32_e32 v4, v197
	s_and_b64 vcc, exec, s[8:9]
	s_cbranch_vccnz .LBB0_484
	s_sub_i32 s6, s2, s1
	s_cmpk_gt_i32 s6, 0xff
	s_cbranch_scc1 .LBB0_484
	v_readlane_b32 s12, v254, 41
	v_readlane_b32 s13, v254, 42
	s_load_dwordx2 s[12:13], s[12:13], 0xa0
	v_lshlrev_b32_e32 v5, 3, v4
	s_waitcnt vmcnt(0)
	v_and_b32_e32 v6, 56, v5
	v_lshlrev_b32_e32 v5, 2, v4
	v_ashrrev_i32_e32 v1, 4, v4
	v_and_b32_e32 v10, 60, v5
	s_movk_i32 s3, 0x110
	v_ashrrev_i32_e32 v3, 3, v4
	v_lshlrev_b32_e32 v5, 2, v10
	v_mul_lo_u32 v7, v1, s3
	s_lshl_b64 s[14:15], s[10:11], 2
	v_add3_u32 v8, 0, v5, v7
	v_add3_u32 v9, 0, v7, v5
	v_lshlrev_b32_e32 v5, 2, v3
	s_waitcnt lgkmcnt(0)
	s_add_u32 s12, s12, s14
	v_and_b32_e32 v5, 0x8c, v5
	s_addc_u32 s13, s13, s15
	v_add_u32_e32 v5, 0, v5
	v_and_b32_e32 v7, 16, v3
	v_and_b32_e32 v4, 0x60, v4
	s_add_u32 s14, s4, 0x3318100
	v_add3_u32 v5, v5, v7, v4
	v_mul_u32_u24_e32 v7, 0x110, v6
	s_addc_u32 s15, s5, 0
	s_lshl_b32 s7, s6, 6
	s_lshl_b32 s22, s0, 6
	v_lshlrev_b32_e32 v4, 2, v10
	v_add_u32_e32 v10, v5, v7
	v_lshlrev_b32_e32 v6, 1, v6
	v_mov_b32_e32 v96, v4
	s_ashr_i32 s60, s6, 31
	s_lshr_b32 s60, s60, 28
	s_add_i32 s60, s6, s60
	s_ashr_i32 s61, s60, 4
	s_lshl_b32 s60, s61, 10
	s_sub_i32 s60, s7, s60
	v_add_u32_e32 v92, s60, v1
	v_ashrrev_i32_e32 v93, 31, v92
	s_lshl_b32 s62, s61, 6
	v_lshlrev_b64 v[88:89], 12, v[92:93]
	v_add_u32_e32 v92, 32, v92
	s_ashr_i32 s63, s62, 31
	v_ashrrev_i32_e32 v93, 31, v92
	v_lshl_add_u64 v[88:89], s[12:13], 0, v[88:89]
	s_lshl_b64 s[64:65], s[62:63], 2
	v_lshlrev_b64 v[92:93], 12, v[92:93]
	v_lshl_add_u64 v[88:89], v[88:89], 0, s[64:65]
	v_mov_b32_e32 v97, v2
	v_lshl_add_u64 v[92:93], s[12:13], 0, v[92:93]
	v_lshl_add_u64 v[88:89], v[88:89], 0, v[96:97]
	v_lshl_add_u64 v[92:93], v[92:93], 0, s[64:65]
	global_load_dwordx4 v[88:91], v[88:89], off
	v_lshl_add_u64 v[92:93], v[92:93], 0, v[96:97]
	global_load_dwordx4 v[92:95], v[92:93], off
	s_waitcnt vmcnt(0)
.LBB0_483:
	s_mov_b32 s16, s60
	s_mov_b32 s17, s61
	s_mov_b32 s18, s62
	s_mov_b32 s19, s63
	s_mov_b32 s20, s64
	s_mov_b32 s21, s65
	s_barrier
	v_add_u32_e32 v5, 0x400, v10
	s_ashr_i32 s17, s16, 31
	v_mov_b32_e32 v7, v2
	s_add_i32 s6, s6, s0
	s_add_i32 s7, s7, s22
	s_cmpk_lt_i32 s6, 0x100
	s_waitcnt vmcnt(2)
	ds_write_b128 v8, v[88:91]
	s_waitcnt vmcnt(1)
	ds_write_b128 v9, v[92:95] offset:8704
	s_cbranch_scc0 .Lcvq4_skip
	v_mov_b32_e32 v96, v4
	s_ashr_i32 s60, s6, 31
	s_lshr_b32 s60, s60, 28
	s_add_i32 s60, s6, s60
	s_ashr_i32 s61, s60, 4
	s_lshl_b32 s60, s61, 10
	s_sub_i32 s60, s7, s60
	v_add_u32_e32 v92, s60, v1
	v_ashrrev_i32_e32 v93, 31, v92
	s_lshl_b32 s62, s61, 6
	v_lshlrev_b64 v[88:89], 12, v[92:93]
	v_add_u32_e32 v92, 32, v92
	s_ashr_i32 s63, s62, 31
	v_ashrrev_i32_e32 v93, 31, v92
	v_lshl_add_u64 v[88:89], s[12:13], 0, v[88:89]
	s_lshl_b64 s[64:65], s[62:63], 2
	v_lshlrev_b64 v[92:93], 12, v[92:93]
	v_lshl_add_u64 v[88:89], v[88:89], 0, s[64:65]
	v_mov_b32_e32 v97, v2
	v_lshl_add_u64 v[92:93], s[12:13], 0, v[92:93]
	v_lshl_add_u64 v[88:89], v[88:89], 0, v[96:97]
	v_lshl_add_u64 v[92:93], v[92:93], 0, s[64:65]
	global_load_dwordx4 v[88:91], v[88:89], off
	v_lshl_add_u64 v[92:93], v[92:93], 0, v[96:97]
	global_load_dwordx4 v[92:95], v[92:93], off
.Lcvq4_skip:
	s_waitcnt lgkmcnt(0)
	s_barrier
	ds_read2_b32 v[16:17], v10 offset1:68
	ds_read2_b32 v[12:13], v10 offset0:136 offset1:204
	ds_read2_b32 v[18:19], v5 offset0:16 offset1:84
	ds_read2_b32 v[14:15], v5 offset0:152 offset1:220
	s_waitcnt lgkmcnt(2)
	v_cvt_pk_f16_f32 v13, v12, v13
	v_cvt_pk_f16_f32 v12, v16, v17
	v_add_u32_e32 v16, s18, v3
	v_ashrrev_i32_e32 v17, 31, v16
	v_lshlrev_b64 v[16:17], 11, v[16:17]
	v_lshl_add_u64 v[16:17], s[14:15], 0, v[16:17]
	v_lshl_add_u64 v[16:17], s[16:17], 1, v[16:17]
	s_waitcnt lgkmcnt(0)
	v_cvt_pk_f16_f32 v15, v14, v15
	v_cvt_pk_f16_f32 v14, v18, v19
	v_lshl_add_u64 v[16:17], v[16:17], 0, v[6:7]
	global_store_dwordx4 v[16:17], v[12:15], off
	s_cmpk_lt_i32 s6, 0x100
	s_cbranch_scc1 .LBB0_483
.LBB0_484:
	v_mov_b32_e32 v4, v197
	s_and_b64 vcc, exec, s[8:9]
	s_cbranch_vccnz .LBB0_488
	s_sub_i32 s6, s2, s1
	s_cmpk_gt_i32 s6, 0xff
	s_cbranch_scc1 .LBB0_488
	v_readlane_b32 s12, v254, 41
	v_readlane_b32 s13, v254, 42
	s_load_dwordx2 s[12:13], s[12:13], 0xf8
	v_ashrrev_i32_e32 v1, 4, v4
	v_ashrrev_i32_e32 v3, 3, v4
	s_lshl_b64 s[10:11], s[10:11], 2
	v_lshlrev_b32_e32 v5, 3, v4
	v_lshlrev_b32_e32 v4, 2, v4
	s_waitcnt lgkmcnt(0)
	s_add_u32 s10, s12, s10
	v_and_b32_e32 v4, 60, v4
	s_movk_i32 s3, 0x110
	s_addc_u32 s11, s13, s11
	s_waitcnt vmcnt(0)
	v_and_b32_e32 v6, 56, v5
	v_lshlrev_b32_e32 v5, 2, v4
	v_mul_lo_u32 v7, v1, s3
	s_add_u32 s12, s4, 0x3518100
	v_add3_u32 v8, 0, v5, v7
	v_add3_u32 v9, 0, v7, v5
	v_lshl_add_u32 v5, v3, 2, 0
	v_mul_u32_u24_e32 v7, 0x110, v6
	s_addc_u32 s13, s5, 0
	s_lshl_b32 s7, s6, 6
	s_lshl_b32 s20, s0, 6
	v_lshlrev_b32_e32 v4, 2, v4
	v_add_u32_e32 v10, v5, v7
	v_lshlrev_b32_e32 v6, 1, v6
	v_mov_b32_e32 v96, v4
	s_ashr_i32 s60, s6, 31
	s_lshr_b32 s60, s60, 28
	s_add_i32 s60, s6, s60
	s_ashr_i32 s61, s60, 4
	s_lshl_b32 s60, s61, 10
	s_sub_i32 s60, s7, s60
	v_add_u32_e32 v92, s60, v1
	v_ashrrev_i32_e32 v93, 31, v92
	s_lshl_b32 s62, s61, 6
	v_lshlrev_b64 v[88:89], 12, v[92:93]
	v_add_u32_e32 v92, 32, v92
	s_ashr_i32 s63, s62, 31
	v_ashrrev_i32_e32 v93, 31, v92
	v_lshl_add_u64 v[88:89], s[10:11], 0, v[88:89]
	s_lshl_b64 s[64:65], s[62:63], 2
	v_lshlrev_b64 v[92:93], 12, v[92:93]
	v_lshl_add_u64 v[88:89], v[88:89], 0, s[64:65]
	v_mov_b32_e32 v97, v2
	v_lshl_add_u64 v[92:93], s[10:11], 0, v[92:93]
	v_lshl_add_u64 v[88:89], v[88:89], 0, v[96:97]
	v_lshl_add_u64 v[92:93], v[92:93], 0, s[64:65]
	global_load_dwordx4 v[88:91], v[88:89], off
	v_lshl_add_u64 v[92:93], v[92:93], 0, v[96:97]
	global_load_dwordx4 v[92:95], v[92:93], off
	s_waitcnt vmcnt(0)
.LBB0_487:
	s_mov_b32 s14, s60
	s_mov_b32 s15, s61
	s_mov_b32 s16, s62
	s_mov_b32 s17, s63
	s_mov_b32 s18, s64
	s_mov_b32 s19, s65
	s_barrier
	v_add_u32_e32 v5, 0x400, v10
	s_ashr_i32 s15, s14, 31
	v_mov_b32_e32 v7, v2
	s_add_i32 s6, s6, s0
	s_add_i32 s7, s7, s20
	s_cmpk_lt_i32 s6, 0x100
	s_waitcnt vmcnt(2)
	ds_write_b128 v8, v[88:91]
	s_waitcnt vmcnt(1)
	ds_write_b128 v9, v[92:95] offset:8704
	s_cbranch_scc0 .Lcvq5_skip
	v_mov_b32_e32 v96, v4
	s_ashr_i32 s60, s6, 31
	s_lshr_b32 s60, s60, 28
	s_add_i32 s60, s6, s60
	s_ashr_i32 s61, s60, 4
	s_lshl_b32 s60, s61, 10
	s_sub_i32 s60, s7, s60
	v_add_u32_e32 v92, s60, v1
	v_ashrrev_i32_e32 v93, 31, v92
	s_lshl_b32 s62, s61, 6
	v_lshlrev_b64 v[88:89], 12, v[92:93]
	v_add_u32_e32 v92, 32, v92
	s_ashr_i32 s63, s62, 31
	v_ashrrev_i32_e32 v93, 31, v92
	v_lshl_add_u64 v[88:89], s[10:11], 0, v[88:89]
	s_lshl_b64 s[64:65], s[62:63], 2
	v_lshlrev_b64 v[92:93], 12, v[92:93]
	v_lshl_add_u64 v[88:89], v[88:89], 0, s[64:65]
	v_mov_b32_e32 v97, v2
	v_lshl_add_u64 v[92:93], s[10:11], 0, v[92:93]
	v_lshl_add_u64 v[88:89], v[88:89], 0, v[96:97]
	v_lshl_add_u64 v[92:93], v[92:93], 0, s[64:65]
	global_load_dwordx4 v[88:91], v[88:89], off
	v_lshl_add_u64 v[92:93], v[92:93], 0, v[96:97]
	global_load_dwordx4 v[92:95], v[92:93], off
.Lcvq5_skip:
	s_waitcnt lgkmcnt(0)
	s_barrier
	ds_read2_b32 v[16:17], v10 offset1:68
	ds_read2_b32 v[12:13], v10 offset0:136 offset1:204
	ds_read2_b32 v[18:19], v5 offset0:16 offset1:84
	ds_read2_b32 v[14:15], v5 offset0:152 offset1:220
	s_waitcnt lgkmcnt(2)
	v_cvt_pk_f16_f32 v13, v12, v13
	v_cvt_pk_f16_f32 v12, v16, v17
	v_add_u32_e32 v16, s16, v3
	v_ashrrev_i32_e32 v17, 31, v16
	v_lshlrev_b64 v[16:17], 11, v[16:17]
	v_lshl_add_u64 v[16:17], s[12:13], 0, v[16:17]
	v_lshl_add_u64 v[16:17], s[14:15], 1, v[16:17]
	s_waitcnt lgkmcnt(0)
	v_cvt_pk_f16_f32 v15, v14, v15
	v_cvt_pk_f16_f32 v14, v18, v19
	v_lshl_add_u64 v[16:17], v[16:17], 0, v[6:7]
	global_store_dwordx4 v[16:17], v[12:15], off
	s_cmpk_lt_i32 s6, 0x100
	s_cbranch_scc1 .LBB0_487
.LBB0_488:
	s_lshl_b64 s[10:11], s[46:47], 19
	v_mov_b32_e32 v4, v197
	s_and_b64 vcc, exec, s[8:9]
	s_cbranch_vccnz .LBB0_492
	s_sub_i32 s6, s2, s1
	s_cmpk_gt_i32 s6, 0x7f
	s_cbranch_scc1 .LBB0_492
	v_readlane_b32 s12, v254, 41
	v_readlane_b32 s13, v254, 42
	s_load_dwordx2 s[12:13], s[12:13], 0xc8
	v_lshlrev_b32_e32 v5, 3, v4
	s_waitcnt vmcnt(0)
	v_and_b32_e32 v6, 56, v5
	v_lshlrev_b32_e32 v5, 2, v4
	v_ashrrev_i32_e32 v1, 4, v4
	v_and_b32_e32 v10, 60, v5
	s_movk_i32 s3, 0x110
	v_ashrrev_i32_e32 v3, 3, v4
	v_lshlrev_b32_e32 v5, 2, v10
	v_mul_lo_u32 v7, v1, s3
	s_lshl_b64 s[14:15], s[10:11], 2
	v_add3_u32 v8, 0, v5, v7
	v_add3_u32 v9, 0, v7, v5
	v_lshlrev_b32_e32 v5, 2, v3
	s_waitcnt lgkmcnt(0)
	s_add_u32 s12, s12, s14
	v_and_b32_e32 v5, 0x8c, v5
	s_addc_u32 s13, s13, s15
	v_add_u32_e32 v5, 0, v5
	v_and_b32_e32 v7, 16, v3
	v_and_b32_e32 v4, 0x60, v4
	s_add_u32 s14, s4, 0x3718100
	v_add3_u32 v5, v5, v7, v4
	v_mul_u32_u24_e32 v7, 0x110, v6
	s_addc_u32 s15, s5, 0
	s_lshl_b32 s7, s6, 6
	s_lshl_b32 s22, s0, 6
	v_lshlrev_b32_e32 v4, 2, v10
	v_add_u32_e32 v10, v5, v7
	v_lshlrev_b32_e32 v6, 1, v6
	v_mov_b32_e32 v96, v4
	s_ashr_i32 s60, s6, 31
	s_lshr_b32 s60, s60, 29
	s_add_i32 s60, s6, s60
	s_ashr_i32 s61, s60, 3
	s_lshl_b32 s60, s61, 9
	s_sub_i32 s60, s7, s60
	v_add_u32_e32 v92, s60, v1
	v_ashrrev_i32_e32 v93, 31, v92
	s_lshl_b32 s62, s61, 6
	v_lshlrev_b64 v[88:89], 12, v[92:93]
	v_add_u32_e32 v92, 32, v92
	s_ashr_i32 s63, s62, 31
	v_ashrrev_i32_e32 v93, 31, v92
	v_lshl_add_u64 v[88:89], s[12:13], 0, v[88:89]
	s_lshl_b64 s[64:65], s[62:63], 2
	v_lshlrev_b64 v[92:93], 12, v[92:93]
	v_lshl_add_u64 v[88:89], v[88:89], 0, s[64:65]
	v_mov_b32_e32 v97, v2
	v_lshl_add_u64 v[92:93], s[12:13], 0, v[92:93]
	v_lshl_add_u64 v[88:89], v[88:89], 0, v[96:97]
	v_lshl_add_u64 v[92:93], v[92:93], 0, s[64:65]
	global_load_dwordx4 v[88:91], v[88:89], off
	v_lshl_add_u64 v[92:93], v[92:93], 0, v[96:97]
	global_load_dwordx4 v[92:95], v[92:93], off
	s_waitcnt vmcnt(0)
.LBB0_491:
	s_mov_b32 s16, s60
	s_mov_b32 s17, s61
	s_mov_b32 s18, s62
	s_mov_b32 s19, s63
	s_mov_b32 s20, s64
	s_mov_b32 s21, s65
	s_barrier
	v_add_u32_e32 v5, 0x400, v10
	s_ashr_i32 s17, s16, 31
	v_mov_b32_e32 v7, v2
	s_add_i32 s6, s6, s0
	s_add_i32 s7, s7, s22
	s_cmpk_lt_i32 s6, 0x80
	s_waitcnt vmcnt(2)
	ds_write_b128 v8, v[88:91]
	s_waitcnt vmcnt(1)
	ds_write_b128 v9, v[92:95] offset:8704
	s_cbranch_scc0 .Lcvq6_skip
	v_mov_b32_e32 v96, v4
	s_ashr_i32 s60, s6, 31
	s_lshr_b32 s60, s60, 29
	s_add_i32 s60, s6, s60
	s_ashr_i32 s61, s60, 3
	s_lshl_b32 s60, s61, 9
	s_sub_i32 s60, s7, s60
	v_add_u32_e32 v92, s60, v1
	v_ashrrev_i32_e32 v93, 31, v92
	s_lshl_b32 s62, s61, 6
	v_lshlrev_b64 v[88:89], 12, v[92:93]
	v_add_u32_e32 v92, 32, v92
	s_ashr_i32 s63, s62, 31
	v_ashrrev_i32_e32 v93, 31, v92
	v_lshl_add_u64 v[88:89], s[12:13], 0, v[88:89]
	s_lshl_b64 s[64:65], s[62:63], 2
	v_lshlrev_b64 v[92:93], 12, v[92:93]
	v_lshl_add_u64 v[88:89], v[88:89], 0, s[64:65]
	v_mov_b32_e32 v97, v2
	v_lshl_add_u64 v[92:93], s[12:13], 0, v[92:93]
	v_lshl_add_u64 v[88:89], v[88:89], 0, v[96:97]
	v_lshl_add_u64 v[92:93], v[92:93], 0, s[64:65]
	global_load_dwordx4 v[88:91], v[88:89], off
	v_lshl_add_u64 v[92:93], v[92:93], 0, v[96:97]
	global_load_dwordx4 v[92:95], v[92:93], off
.Lcvq6_skip:
	s_waitcnt lgkmcnt(0)
	s_barrier
	ds_read2_b32 v[16:17], v10 offset1:68
	ds_read2_b32 v[12:13], v10 offset0:136 offset1:204
	ds_read2_b32 v[18:19], v5 offset0:16 offset1:84
	ds_read2_b32 v[14:15], v5 offset0:152 offset1:220
	s_waitcnt lgkmcnt(2)
	v_cvt_pk_f16_f32 v13, v12, v13
	v_cvt_pk_f16_f32 v12, v16, v17
	v_add_u32_e32 v16, s18, v3
	v_ashrrev_i32_e32 v17, 31, v16
	v_lshlrev_b64 v[16:17], 10, v[16:17]
	v_lshl_add_u64 v[16:17], s[14:15], 0, v[16:17]
	v_lshl_add_u64 v[16:17], s[16:17], 1, v[16:17]
	s_waitcnt lgkmcnt(0)
	v_cvt_pk_f16_f32 v15, v14, v15
	v_cvt_pk_f16_f32 v14, v18, v19
	v_lshl_add_u64 v[16:17], v[16:17], 0, v[6:7]
	global_store_dwordx4 v[16:17], v[12:15], off
	s_cmpk_lt_i32 s6, 0x80
	s_cbranch_scc1 .LBB0_491
.LBB0_492:
	v_mov_b32_e32 v4, v197
	s_and_b64 vcc, exec, s[8:9]
	s_cbranch_vccnz .LBB0_496
	s_sub_i32 s6, s2, s1
	s_cmpk_gt_i32 s6, 0x7f
	s_cbranch_scc1 .LBB0_496
	v_readlane_b32 s12, v254, 41
	v_readlane_b32 s13, v254, 42
	s_load_dwordx2 s[12:13], s[12:13], 0xf0
	v_lshlrev_b32_e32 v5, 3, v4
	s_waitcnt vmcnt(0)
	v_and_b32_e32 v6, 56, v5
	v_lshlrev_b32_e32 v5, 2, v4
	v_ashrrev_i32_e32 v1, 4, v4
	v_and_b32_e32 v10, 60, v5
	s_movk_i32 s3, 0x110
	v_ashrrev_i32_e32 v3, 3, v4
	v_lshlrev_b32_e32 v5, 2, v10
	v_mul_lo_u32 v7, v1, s3
	s_lshl_b64 s[14:15], s[10:11], 2
	v_add3_u32 v8, 0, v5, v7
	v_add3_u32 v9, 0, v7, v5
	v_lshlrev_b32_e32 v5, 2, v3
	s_waitcnt lgkmcnt(0)
	s_add_u32 s12, s12, s14
	v_and_b32_e32 v5, 0x8c, v5
	s_addc_u32 s13, s13, s15
	v_add_u32_e32 v5, 0, v5
	v_and_b32_e32 v7, 16, v3
	v_and_b32_e32 v4, 0x60, v4
	s_add_u32 s14, s4, 0x3818100
	v_add3_u32 v5, v5, v7, v4
	v_mul_u32_u24_e32 v7, 0x110, v6
	s_addc_u32 s15, s5, 0
	s_lshl_b32 s7, s6, 6
	s_lshl_b32 s22, s0, 6
	v_lshlrev_b32_e32 v4, 2, v10
	v_add_u32_e32 v10, v5, v7
	v_lshlrev_b32_e32 v6, 1, v6
	v_mov_b32_e32 v96, v4
	s_ashr_i32 s60, s6, 31
	s_lshr_b32 s60, s60, 29
	s_add_i32 s60, s6, s60
	s_ashr_i32 s61, s60, 3
	s_lshl_b32 s60, s61, 9
	s_sub_i32 s60, s7, s60
	v_add_u32_e32 v92, s60, v1
	v_ashrrev_i32_e32 v93, 31, v92
	s_lshl_b32 s62, s61, 6
	v_lshlrev_b64 v[88:89], 12, v[92:93]
	v_add_u32_e32 v92, 32, v92
	s_ashr_i32 s63, s62, 31
	v_ashrrev_i32_e32 v93, 31, v92
	v_lshl_add_u64 v[88:89], s[12:13], 0, v[88:89]
	s_lshl_b64 s[64:65], s[62:63], 2
	v_lshlrev_b64 v[92:93], 12, v[92:93]
	v_lshl_add_u64 v[88:89], v[88:89], 0, s[64:65]
	v_mov_b32_e32 v97, v2
	v_lshl_add_u64 v[92:93], s[12:13], 0, v[92:93]
	v_lshl_add_u64 v[88:89], v[88:89], 0, v[96:97]
	v_lshl_add_u64 v[92:93], v[92:93], 0, s[64:65]
	global_load_dwordx4 v[88:91], v[88:89], off
	v_lshl_add_u64 v[92:93], v[92:93], 0, v[96:97]
	global_load_dwordx4 v[92:95], v[92:93], off
	s_waitcnt vmcnt(0)
